# s5_pass2 GELU: tanh(|u|) = 1 - 2/(1+exp2(2|u|log2e)) with v_exp/v_rcp, straight-line (was a divergent two-branch libm tanhf per element)
# speedup vs baseline: 1.0048x; 1.0048x over previous
.LBB0_651:
	s_mov_b32 s7, 0xffff2000
	v_add_co_u32_e32 v80, vcc, s7, v32
	s_mov_b32 s7, 0xffff4000
	s_nop 0
	v_addc_co_u32_e32 v81, vcc, -1, v33, vcc
	v_add_co_u32_e32 v88, vcc, s7, v32
	s_mov_b32 s7, 0xffff6000
	s_nop 0
	v_addc_co_u32_e32 v89, vcc, -1, v33, vcc
	v_add_co_u32_e32 v96, vcc, s7, v32
	s_movk_i32 s7, 0xa000
	s_nop 0
	v_addc_co_u32_e32 v97, vcc, -1, v33, vcc
	v_add_co_u32_e32 v104, vcc, s77, v32
	s_nop 1
	v_addc_co_u32_e32 v105, vcc, -1, v33, vcc
	v_add_co_u32_e32 v112, vcc, s7, v32
	s_movk_i32 s7, 0xc000
	s_nop 0
	v_addc_co_u32_e32 v113, vcc, -1, v33, vcc
	v_add_co_u32_e32 v120, vcc, s7, v32
	s_movk_i32 s7, 0xe000
	s_nop 0
	v_addc_co_u32_e32 v121, vcc, -1, v33, vcc
	v_add_co_u32_e32 v128, vcc, s7, v32
	s_nop 1
	v_addc_co_u32_e32 v129, vcc, -1, v33, vcc
	global_load_dwordx4 v[76:79], v[80:81], off offset:-1024
	s_nop 0
	global_load_dwordx4 v[80:83], v[80:81], off
	s_nop 0
	global_load_dwordx4 v[84:87], v[88:89], off offset:-1024
	s_nop 0
	global_load_dwordx4 v[88:91], v[88:89], off
	s_nop 0
	global_load_dwordx4 v[92:95], v[96:97], off offset:-1024
	s_nop 0
	global_load_dwordx4 v[96:99], v[96:97], off
	s_nop 0
	global_load_dwordx4 v[100:103], v[104:105], off offset:-1024
	s_nop 0
	global_load_dwordx4 v[104:107], v[104:105], off
	s_nop 0
	global_load_dwordx4 v[108:111], v[112:113], off offset:-1024
	s_nop 0
	global_load_dwordx4 v[112:115], v[112:113], off
	s_nop 0
	global_load_dwordx4 v[116:119], v[120:121], off offset:-1024
	s_nop 0
	global_load_dwordx4 v[120:123], v[120:121], off
	s_nop 0
	global_load_dwordx4 v[124:127], v[128:129], off offset:-1024
	s_nop 0
	global_load_dwordx4 v[128:131], v[128:129], off
	s_nop 0
	global_load_dwordx4 v[132:135], v[32:33], off offset:-1024
	global_load_dwordx4 v[136:139], v[32:33], off
	s_mov_b64 s[12:13], 0x800
	v_lshl_add_u64 v[32:33], v[32:33], 0, s[12:13]
	s_mov_b32 s7, 0xffff2000
	v_add_co_u32_e32 v148, vcc, s7, v32
	s_mov_b32 s7, 0xffff4000
	s_nop 0
	v_addc_co_u32_e32 v149, vcc, -1, v33, vcc
	v_add_co_u32_e32 v156, vcc, s7, v32
	s_mov_b32 s7, 0xffff6000
	s_nop 0
	v_addc_co_u32_e32 v157, vcc, -1, v33, vcc
	v_add_co_u32_e32 v176, vcc, s7, v32
	s_movk_i32 s7, 0xa000
	s_nop 0
	v_addc_co_u32_e32 v177, vcc, -1, v33, vcc
	v_add_co_u32_e32 v184, vcc, s77, v32
	s_nop 1
	v_addc_co_u32_e32 v185, vcc, -1, v33, vcc
	v_add_co_u32_e32 v200, vcc, s7, v32
	s_movk_i32 s7, 0xc000
	s_nop 0
	v_addc_co_u32_e32 v201, vcc, -1, v33, vcc
	v_add_co_u32_e32 v208, vcc, s7, v32
	s_movk_i32 s7, 0xe000
	s_nop 0
	v_addc_co_u32_e32 v209, vcc, -1, v33, vcc
	v_add_co_u32_e32 v240, vcc, s7, v32
	s_nop 1
	v_addc_co_u32_e32 v241, vcc, -1, v33, vcc
	global_load_dwordx4 v[144:147], v[148:149], off offset:-1024
	s_nop 0
	global_load_dwordx4 v[148:151], v[148:149], off
	s_nop 0
	global_load_dwordx4 v[152:155], v[156:157], off offset:-1024
	s_nop 0
	global_load_dwordx4 v[156:159], v[156:157], off
	s_nop 0
	global_load_dwordx4 v[172:175], v[176:177], off offset:-1024
	s_nop 0
	global_load_dwordx4 v[176:179], v[176:177], off
	s_nop 0
	global_load_dwordx4 v[180:183], v[184:185], off offset:-1024
	s_nop 0
	global_load_dwordx4 v[184:187], v[184:185], off
	s_nop 0
	global_load_dwordx4 v[196:199], v[200:201], off offset:-1024
	s_nop 0
	global_load_dwordx4 v[200:203], v[200:201], off
	s_nop 0
	global_load_dwordx4 v[204:207], v[208:209], off offset:-1024
	s_nop 0
	global_load_dwordx4 v[208:211], v[208:209], off
	s_nop 0
	global_load_dwordx4 v[236:239], v[240:241], off offset:-1024
	s_nop 0
	global_load_dwordx4 v[240:243], v[240:241], off
	s_nop 0
	global_load_dwordx4 v[244:247], v[32:33], off offset:-1024
	global_load_dwordx4 v[248:251], v[32:33], off
	s_mov_b64 s[12:13], 0x800
	v_lshl_add_u64 v[32:33], v[32:33], 0, s[12:13]
	ds_read_b128 v[140:143], v34
	s_waitcnt vmcnt(31) lgkmcnt(0)
	v_mfma_f32_16x16x32_bf16 v[28:31], v[76:79], v[140:143], v[28:31]
	ds_read_b128 v[76:79], v34 offset:64
	s_waitcnt vmcnt(29)
	v_mfma_f32_16x16x32_bf16 v[24:27], v[84:87], v[140:143], v[24:27]
	s_waitcnt vmcnt(27)
	v_mfma_f32_16x16x32_bf16 v[20:23], v[92:95], v[140:143], v[20:23]
	s_waitcnt vmcnt(25)
	v_mfma_f32_16x16x32_bf16 v[16:19], v[100:103], v[140:143], v[16:19]
	s_waitcnt vmcnt(23)
	v_mfma_f32_16x16x32_bf16 v[12:15], v[108:111], v[140:143], v[12:15]
	s_waitcnt vmcnt(21)
	v_mfma_f32_16x16x32_bf16 v[8:11], v[116:119], v[140:143], v[8:11]
	s_waitcnt vmcnt(19)
	v_mfma_f32_16x16x32_bf16 v[4:7], v[124:127], v[140:143], v[4:7]
	s_waitcnt vmcnt(17)
	v_mfma_f32_16x16x32_bf16 v[0:3], v[132:135], v[140:143], v[0:3]
	s_waitcnt lgkmcnt(0)
	v_mfma_f32_16x16x32_bf16 v[28:31], v[80:83], v[76:79], v[28:31]
	v_mfma_f32_16x16x32_bf16 v[24:27], v[88:91], v[76:79], v[24:27]
	v_mfma_f32_16x16x32_bf16 v[20:23], v[96:99], v[76:79], v[20:23]
	v_mfma_f32_16x16x32_bf16 v[16:19], v[104:107], v[76:79], v[16:19]
	v_mfma_f32_16x16x32_bf16 v[12:15], v[112:115], v[76:79], v[12:15]
	v_mfma_f32_16x16x32_bf16 v[8:11], v[120:123], v[76:79], v[8:11]
	v_mfma_f32_16x16x32_bf16 v[4:7], v[128:131], v[76:79], v[4:7]
	s_waitcnt vmcnt(16)
	v_mfma_f32_16x16x32_bf16 v[0:3], v[136:139], v[76:79], v[0:3]
	v_add_u32_e32 v34, 0x80, v34
	s_mov_b32 s7, 0xffff2000
	v_add_co_u32_e32 v80, vcc, s7, v32
	s_mov_b32 s7, 0xffff4000
	s_nop 0
	v_addc_co_u32_e32 v81, vcc, -1, v33, vcc
	v_add_co_u32_e32 v88, vcc, s7, v32
	s_mov_b32 s7, 0xffff6000
	s_nop 0
	v_addc_co_u32_e32 v89, vcc, -1, v33, vcc
	v_add_co_u32_e32 v96, vcc, s7, v32
	s_movk_i32 s7, 0xa000
	s_nop 0
	v_addc_co_u32_e32 v97, vcc, -1, v33, vcc
	v_add_co_u32_e32 v104, vcc, s77, v32
	s_nop 1
	v_addc_co_u32_e32 v105, vcc, -1, v33, vcc
	v_add_co_u32_e32 v112, vcc, s7, v32
	s_movk_i32 s7, 0xc000
	s_nop 0
	v_addc_co_u32_e32 v113, vcc, -1, v33, vcc
	v_add_co_u32_e32 v120, vcc, s7, v32
	s_movk_i32 s7, 0xe000
	s_nop 0
	v_addc_co_u32_e32 v121, vcc, -1, v33, vcc
	v_add_co_u32_e32 v128, vcc, s7, v32
	s_nop 1
	v_addc_co_u32_e32 v129, vcc, -1, v33, vcc
	global_load_dwordx4 v[76:79], v[80:81], off offset:-1024
	s_nop 0
	global_load_dwordx4 v[80:83], v[80:81], off
	s_nop 0
	global_load_dwordx4 v[84:87], v[88:89], off offset:-1024
	s_nop 0
	global_load_dwordx4 v[88:91], v[88:89], off
	s_nop 0
	global_load_dwordx4 v[92:95], v[96:97], off offset:-1024
	s_nop 0
	global_load_dwordx4 v[96:99], v[96:97], off
	s_nop 0
	global_load_dwordx4 v[100:103], v[104:105], off offset:-1024
	s_nop 0
	global_load_dwordx4 v[104:107], v[104:105], off
	s_nop 0
	global_load_dwordx4 v[108:111], v[112:113], off offset:-1024
	s_nop 0
	global_load_dwordx4 v[112:115], v[112:113], off
	s_nop 0
	global_load_dwordx4 v[116:119], v[120:121], off offset:-1024
	s_nop 0
	global_load_dwordx4 v[120:123], v[120:121], off
	s_nop 0
	global_load_dwordx4 v[124:127], v[128:129], off offset:-1024
	s_nop 0
	global_load_dwordx4 v[128:131], v[128:129], off
	s_nop 0
	global_load_dwordx4 v[132:135], v[32:33], off offset:-1024
	global_load_dwordx4 v[136:139], v[32:33], off
	s_mov_b64 s[12:13], 0x800
	v_lshl_add_u64 v[32:33], v[32:33], 0, s[12:13]
	ds_read_b128 v[140:143], v34
	s_waitcnt vmcnt(31) lgkmcnt(0)
	v_mfma_f32_16x16x32_bf16 v[28:31], v[144:147], v[140:143], v[28:31]
	ds_read_b128 v[144:147], v34 offset:64
	s_waitcnt vmcnt(29)
	v_mfma_f32_16x16x32_bf16 v[24:27], v[152:155], v[140:143], v[24:27]
	s_waitcnt vmcnt(27)
	v_mfma_f32_16x16x32_bf16 v[20:23], v[172:175], v[140:143], v[20:23]
	s_waitcnt vmcnt(25)
	v_mfma_f32_16x16x32_bf16 v[16:19], v[180:183], v[140:143], v[16:19]
	s_waitcnt vmcnt(23)
	v_mfma_f32_16x16x32_bf16 v[12:15], v[196:199], v[140:143], v[12:15]
	s_waitcnt vmcnt(21)
	v_mfma_f32_16x16x32_bf16 v[8:11], v[204:207], v[140:143], v[8:11]
	s_waitcnt vmcnt(19)
	v_mfma_f32_16x16x32_bf16 v[4:7], v[236:239], v[140:143], v[4:7]
	s_waitcnt vmcnt(17)
	v_mfma_f32_16x16x32_bf16 v[0:3], v[244:247], v[140:143], v[0:3]
	s_waitcnt lgkmcnt(0)
	v_mfma_f32_16x16x32_bf16 v[28:31], v[148:151], v[144:147], v[28:31]
	v_mfma_f32_16x16x32_bf16 v[24:27], v[156:159], v[144:147], v[24:27]
	v_mfma_f32_16x16x32_bf16 v[20:23], v[176:179], v[144:147], v[20:23]
	v_mfma_f32_16x16x32_bf16 v[16:19], v[184:187], v[144:147], v[16:19]
	v_mfma_f32_16x16x32_bf16 v[12:15], v[200:203], v[144:147], v[12:15]
	v_mfma_f32_16x16x32_bf16 v[8:11], v[208:211], v[144:147], v[8:11]
	v_mfma_f32_16x16x32_bf16 v[4:7], v[240:243], v[144:147], v[4:7]
	s_waitcnt vmcnt(16)
	v_mfma_f32_16x16x32_bf16 v[0:3], v[248:251], v[144:147], v[0:3]
	v_add_u32_e32 v34, 0x80, v34
	s_mov_b32 s7, 0xffff2000
	v_add_co_u32_e32 v148, vcc, s7, v32
	s_mov_b32 s7, 0xffff4000
	s_nop 0
	v_addc_co_u32_e32 v149, vcc, -1, v33, vcc
	v_add_co_u32_e32 v156, vcc, s7, v32
	s_mov_b32 s7, 0xffff6000
	s_nop 0
	v_addc_co_u32_e32 v157, vcc, -1, v33, vcc
	v_add_co_u32_e32 v176, vcc, s7, v32
	s_movk_i32 s7, 0xa000
	s_nop 0
	v_addc_co_u32_e32 v177, vcc, -1, v33, vcc
	v_add_co_u32_e32 v184, vcc, s77, v32
	s_nop 1
	v_addc_co_u32_e32 v185, vcc, -1, v33, vcc
	v_add_co_u32_e32 v200, vcc, s7, v32
	s_movk_i32 s7, 0xc000
	s_nop 0
	v_addc_co_u32_e32 v201, vcc, -1, v33, vcc
	v_add_co_u32_e32 v208, vcc, s7, v32
	s_movk_i32 s7, 0xe000
	s_nop 0
	v_addc_co_u32_e32 v209, vcc, -1, v33, vcc
	v_add_co_u32_e32 v240, vcc, s7, v32
	s_nop 1
	v_addc_co_u32_e32 v241, vcc, -1, v33, vcc
	global_load_dwordx4 v[144:147], v[148:149], off offset:-1024
	s_nop 0
	global_load_dwordx4 v[148:151], v[148:149], off
	s_nop 0
	global_load_dwordx4 v[152:155], v[156:157], off offset:-1024
	s_nop 0
	global_load_dwordx4 v[156:159], v[156:157], off
	s_nop 0
	global_load_dwordx4 v[172:175], v[176:177], off offset:-1024
	s_nop 0
	global_load_dwordx4 v[176:179], v[176:177], off
	s_nop 0
	global_load_dwordx4 v[180:183], v[184:185], off offset:-1024
	s_nop 0
	global_load_dwordx4 v[184:187], v[184:185], off
	s_nop 0
	global_load_dwordx4 v[196:199], v[200:201], off offset:-1024
	s_nop 0
	global_load_dwordx4 v[200:203], v[200:201], off
	s_nop 0
	global_load_dwordx4 v[204:207], v[208:209], off offset:-1024
	s_nop 0
	global_load_dwordx4 v[208:211], v[208:209], off
	s_nop 0
	global_load_dwordx4 v[236:239], v[240:241], off offset:-1024
	s_nop 0
	global_load_dwordx4 v[240:243], v[240:241], off
	s_nop 0
	global_load_dwordx4 v[244:247], v[32:33], off offset:-1024
	global_load_dwordx4 v[248:251], v[32:33], off
	ds_read_b128 v[140:143], v34
	s_waitcnt vmcnt(31) lgkmcnt(0)
	v_mfma_f32_16x16x32_bf16 v[28:31], v[76:79], v[140:143], v[28:31]
	ds_read_b128 v[76:79], v34 offset:64
	s_waitcnt vmcnt(29)
	v_mfma_f32_16x16x32_bf16 v[24:27], v[84:87], v[140:143], v[24:27]
	s_waitcnt vmcnt(27)
	v_mfma_f32_16x16x32_bf16 v[20:23], v[92:95], v[140:143], v[20:23]
	s_waitcnt vmcnt(25)
	v_mfma_f32_16x16x32_bf16 v[16:19], v[100:103], v[140:143], v[16:19]
	s_waitcnt vmcnt(23)
	v_mfma_f32_16x16x32_bf16 v[12:15], v[108:111], v[140:143], v[12:15]
	s_waitcnt vmcnt(21)
	v_mfma_f32_16x16x32_bf16 v[8:11], v[116:119], v[140:143], v[8:11]
	s_waitcnt vmcnt(19)
	v_mfma_f32_16x16x32_bf16 v[4:7], v[124:127], v[140:143], v[4:7]
	s_waitcnt vmcnt(17)
	v_mfma_f32_16x16x32_bf16 v[0:3], v[132:135], v[140:143], v[0:3]
	s_waitcnt lgkmcnt(0)
	v_mfma_f32_16x16x32_bf16 v[28:31], v[80:83], v[76:79], v[28:31]
	v_mfma_f32_16x16x32_bf16 v[24:27], v[88:91], v[76:79], v[24:27]
	v_mfma_f32_16x16x32_bf16 v[20:23], v[96:99], v[76:79], v[20:23]
	v_mfma_f32_16x16x32_bf16 v[16:19], v[104:107], v[76:79], v[16:19]
	v_mfma_f32_16x16x32_bf16 v[12:15], v[112:115], v[76:79], v[12:15]
	v_mfma_f32_16x16x32_bf16 v[8:11], v[120:123], v[76:79], v[8:11]
	v_mfma_f32_16x16x32_bf16 v[4:7], v[128:131], v[76:79], v[4:7]
	s_waitcnt vmcnt(16)
	v_mfma_f32_16x16x32_bf16 v[0:3], v[136:139], v[76:79], v[0:3]
	v_add_u32_e32 v34, 0x80, v34
	ds_read_b128 v[140:143], v34
	s_waitcnt vmcnt(15) lgkmcnt(0)
	v_mfma_f32_16x16x32_bf16 v[28:31], v[144:147], v[140:143], v[28:31]
	ds_read_b128 v[144:147], v34 offset:64
	s_waitcnt vmcnt(13)
	v_mfma_f32_16x16x32_bf16 v[24:27], v[152:155], v[140:143], v[24:27]
	s_waitcnt vmcnt(11)
	v_mfma_f32_16x16x32_bf16 v[20:23], v[172:175], v[140:143], v[20:23]
	s_waitcnt vmcnt(9)
	v_mfma_f32_16x16x32_bf16 v[16:19], v[180:183], v[140:143], v[16:19]
	s_waitcnt vmcnt(7)
	v_mfma_f32_16x16x32_bf16 v[12:15], v[196:199], v[140:143], v[12:15]
	s_waitcnt vmcnt(5)
	v_mfma_f32_16x16x32_bf16 v[8:11], v[204:207], v[140:143], v[8:11]
	s_waitcnt vmcnt(3)
	v_mfma_f32_16x16x32_bf16 v[4:7], v[236:239], v[140:143], v[4:7]
	s_waitcnt vmcnt(1)
	v_mfma_f32_16x16x32_bf16 v[0:3], v[244:247], v[140:143], v[0:3]
	s_waitcnt lgkmcnt(0)
	v_mfma_f32_16x16x32_bf16 v[28:31], v[148:151], v[144:147], v[28:31]
	v_mfma_f32_16x16x32_bf16 v[24:27], v[156:159], v[144:147], v[24:27]
	v_mfma_f32_16x16x32_bf16 v[20:23], v[176:179], v[144:147], v[20:23]
	v_mfma_f32_16x16x32_bf16 v[16:19], v[184:187], v[144:147], v[16:19]
	v_mfma_f32_16x16x32_bf16 v[12:15], v[200:203], v[144:147], v[12:15]
	v_mfma_f32_16x16x32_bf16 v[8:11], v[208:211], v[144:147], v[8:11]
	v_mfma_f32_16x16x32_bf16 v[4:7], v[240:243], v[144:147], v[4:7]
	s_waitcnt vmcnt(0)
	v_mfma_f32_16x16x32_bf16 v[0:3], v[248:251], v[144:147], v[0:3]
	v_mul_f32_e32 v32, 0x3d372713, v28
	v_mul_f32_e32 v32, v28, v32
	v_fma_f32 v32, v28, v32, v28
	v_mul_f32_e32 v32, 0x3f4c422a, v32
	s_mov_b32 s6, 0x4038aa3b
	v_mul_f32_e64 v33, |v32|, s6
	v_exp_f32_e32 v33, v33
	s_nop 0
	v_add_f32_e32 v33, 1.0, v33
	v_rcp_f32_e32 v33, v33
	s_nop 0
	v_fma_f32 v33, v33, -2.0, 1.0
	v_mul_f32_e32 v34, 0x3d372713, v29
	v_mul_f32_e32 v34, v29, v34
	v_fma_f32 v34, v29, v34, v29
	v_mul_f32_e32 v34, 0x3f4c422a, v34
	s_mov_b32 s6, 0x4038aa3b
	v_mul_f32_e64 v35, |v34|, s6
	v_exp_f32_e32 v35, v35
	s_nop 0
	v_add_f32_e32 v35, 1.0, v35
	v_rcp_f32_e32 v35, v35
	s_nop 0
	v_fma_f32 v35, v35, -2.0, 1.0
	s_brev_b32 s6, -2
	v_bfi_b32 v32, s6, v33, v32
	v_mul_f32_e32 v28, 0.5, v28
	v_add_f32_e32 v32, 1.0, v32
	v_mul_f32_e32 v28, v28, v32
	v_bfi_b32 v32, s6, v35, v34
	v_mul_f32_e32 v29, 0.5, v29
	v_add_f32_e32 v32, 1.0, v32
	v_mul_f32_e32 v29, v29, v32
	v_cvt_pk_bf16_f32 v32, v28, v29
	v_mul_f32_e32 v28, 0x3d372713, v30
	v_mul_f32_e32 v28, v30, v28
	v_fma_f32 v28, v30, v28, v30
	v_mul_f32_e32 v28, 0x3f4c422a, v28
	s_mov_b32 s6, 0x4038aa3b
	v_mul_f32_e64 v29, |v28|, s6
	v_exp_f32_e32 v29, v29
	s_nop 0
	v_add_f32_e32 v29, 1.0, v29
	v_rcp_f32_e32 v29, v29
	s_nop 0
	v_fma_f32 v29, v29, -2.0, 1.0
	v_mul_f32_e32 v33, 0x3d372713, v31
	v_mul_f32_e32 v33, v31, v33
	v_fma_f32 v33, v31, v33, v31
	v_mul_f32_e32 v33, 0x3f4c422a, v33
	s_mov_b32 s6, 0x4038aa3b
	v_mul_f32_e64 v34, |v33|, s6
	v_exp_f32_e32 v34, v34
	s_nop 0
	v_add_f32_e32 v34, 1.0, v34
	v_rcp_f32_e32 v34, v34
	s_nop 0
	v_fma_f32 v34, v34, -2.0, 1.0
	s_brev_b32 s12, -2
	v_bfi_b32 v28, s12, v29, v28
	v_mul_f32_e32 v30, 0.5, v30
	v_add_f32_e32 v28, 1.0, v28
	v_mul_f32_e32 v35, v30, v28
	v_or_b32_e32 v28, s11, v60
	v_mul_hi_i32 v29, v28, s16
	v_lshrrev_b32_e32 v30, 31, v29
	v_ashrrev_i32_e32 v29, 5, v29
	v_add_u32_e32 v30, v29, v30
	v_mad_u64_u32 v[28:29], s[6:7], v30, s18, v[28:29]
	v_lshl_add_u32 v29, v30, 8, v228
	v_lshl_add_u32 v30, v30, 12, v229
	v_cmp_gt_i32_e32 vcc, 4, v28
	v_bfi_b32 v33, s12, v34, v33
	v_lshlrev_b32_e32 v76, 6, v28
	v_cndmask_b32_e32 v28, v30, v29, vcc
	v_mul_f32_e32 v31, 0.5, v31
	v_add_f32_e32 v33, 1.0, v33
	v_add3_u32 v30, v76, v40, v28
	v_mul_f32_e32 v31, v31, v33
	v_cvt_pk_bf16_f32 v33, v35, v31
	v_ashrrev_i32_e32 v31, 31, v30
	v_lshlrev_b64 v[34:35], 11, v[30:31]
	v_mul_f32_e32 v31, 0x3d372713, v24
	v_mul_f32_e32 v31, v24, v31
	v_fma_f32 v31, v24, v31, v24
	v_lshl_add_u64 v[28:29], s[4:5], 1, v[42:43]
	v_mul_f32_e32 v31, 0x3f4c422a, v31
	s_mov_b32 s4, 0x4038aa3b
	v_lshl_add_u64 v[34:35], v[28:29], 0, v[34:35]
	global_store_dwordx2 v[34:35], v[32:33], off
	v_mul_f32_e64 v32, |v31|, s4
	v_exp_f32_e32 v32, v32
	s_nop 0
	v_add_f32_e32 v32, 1.0, v32
	v_rcp_f32_e32 v32, v32
	s_nop 0
	v_fma_f32 v32, v32, -2.0, 1.0
	v_mul_f32_e32 v33, 0x3d372713, v25
	v_mul_f32_e32 v33, v25, v33
	v_fma_f32 v33, v25, v33, v25
	v_mul_f32_e32 v33, 0x3f4c422a, v33
	s_mov_b32 s4, 0x4038aa3b
	v_mul_f32_e64 v34, |v33|, s4
	v_exp_f32_e32 v34, v34
	s_nop 0
	v_add_f32_e32 v34, 1.0, v34
	v_rcp_f32_e32 v34, v34
	s_nop 0
	v_fma_f32 v34, v34, -2.0, 1.0
	s_brev_b32 s4, -2
	v_bfi_b32 v31, s4, v32, v31
	v_mul_f32_e32 v24, 0.5, v24
	v_add_f32_e32 v31, 1.0, v31
	v_mul_f32_e32 v24, v24, v31
	v_bfi_b32 v31, s4, v34, v33
	v_mul_f32_e32 v25, 0.5, v25
	v_add_f32_e32 v31, 1.0, v31
	v_mul_f32_e32 v25, v25, v31
	v_cvt_pk_bf16_f32 v24, v24, v25
	v_mul_f32_e32 v25, 0x3d372713, v26
	v_mul_f32_e32 v25, v26, v25
	v_fma_f32 v25, v26, v25, v26
	v_mul_f32_e32 v25, 0x3f4c422a, v25
	s_mov_b32 s4, 0x4038aa3b
	v_mul_f32_e64 v31, |v25|, s4
	v_exp_f32_e32 v31, v31
	s_nop 0
	v_add_f32_e32 v31, 1.0, v31
	v_rcp_f32_e32 v31, v31
	s_nop 0
	v_fma_f32 v31, v31, -2.0, 1.0
	v_mul_f32_e32 v32, 0x3d372713, v27
	v_mul_f32_e32 v32, v27, v32
	v_fma_f32 v32, v27, v32, v27
	v_mul_f32_e32 v32, 0x3f4c422a, v32
	s_mov_b32 s4, 0x4038aa3b
	v_mul_f32_e64 v33, |v32|, s4
	v_exp_f32_e32 v33, v33
	s_nop 0
	v_add_f32_e32 v33, 1.0, v33
	v_rcp_f32_e32 v33, v33
	s_nop 0
	v_fma_f32 v33, v33, -2.0, 1.0
	s_brev_b32 s4, -2
	v_bfi_b32 v25, s4, v31, v25
	v_mul_f32_e32 v26, 0.5, v26
	v_add_f32_e32 v25, 1.0, v25
	v_mul_f32_e32 v25, v26, v25
	v_mul_f32_e32 v26, 0.5, v27
	v_bfi_b32 v27, s4, v33, v32
	v_add_f32_e32 v27, 1.0, v27
	v_mul_f32_e32 v26, v26, v27
	v_cvt_pk_bf16_f32 v25, v25, v26
	v_or_b32_e32 v26, 1, v30
	v_ashrrev_i32_e32 v27, 31, v26
	v_lshlrev_b64 v[26:27], 11, v[26:27]
	v_lshl_add_u64 v[26:27], v[28:29], 0, v[26:27]
	global_store_dwordx2 v[26:27], v[24:25], off
	v_mul_f32_e32 v24, 0x3d372713, v20
	v_mul_f32_e32 v24, v20, v24
	v_fma_f32 v24, v20, v24, v20
	v_mul_f32_e32 v24, 0x3f4c422a, v24
	s_mov_b32 s4, 0x4038aa3b
	v_mul_f32_e64 v25, |v24|, s4
	v_exp_f32_e32 v25, v25
	s_nop 0
	v_add_f32_e32 v25, 1.0, v25
	v_rcp_f32_e32 v25, v25
	s_nop 0
	v_fma_f32 v25, v25, -2.0, 1.0
	v_mul_f32_e32 v26, 0x3d372713, v21
	v_mul_f32_e32 v26, v21, v26
	v_fma_f32 v26, v21, v26, v21
	v_mul_f32_e32 v26, 0x3f4c422a, v26
	s_mov_b32 s4, 0x4038aa3b
	v_mul_f32_e64 v27, |v26|, s4
	v_exp_f32_e32 v27, v27
	s_nop 0
	v_add_f32_e32 v27, 1.0, v27
	v_rcp_f32_e32 v27, v27
	s_nop 0
	v_fma_f32 v27, v27, -2.0, 1.0
	s_brev_b32 s4, -2
	v_bfi_b32 v24, s4, v25, v24
	v_mul_f32_e32 v20, 0.5, v20
	v_add_f32_e32 v24, 1.0, v24
	v_mul_f32_e32 v20, v20, v24
	v_bfi_b32 v24, s4, v27, v26
	v_mul_f32_e32 v21, 0.5, v21
	v_add_f32_e32 v24, 1.0, v24
	v_mul_f32_e32 v21, v21, v24
	v_cvt_pk_bf16_f32 v20, v20, v21
	v_mul_f32_e32 v21, 0x3d372713, v22
	v_mul_f32_e32 v21, v22, v21
	v_fma_f32 v21, v22, v21, v22
	v_mul_f32_e32 v21, 0x3f4c422a, v21
	s_mov_b32 s4, 0x4038aa3b
	v_mul_f32_e64 v24, |v21|, s4
	v_exp_f32_e32 v24, v24
	s_nop 0
	v_add_f32_e32 v24, 1.0, v24
	v_rcp_f32_e32 v24, v24
	s_nop 0
	v_fma_f32 v24, v24, -2.0, 1.0
	v_mul_f32_e32 v25, 0x3d372713, v23
	v_mul_f32_e32 v25, v23, v25
	v_fma_f32 v25, v23, v25, v23
	v_mul_f32_e32 v25, 0x3f4c422a, v25
	s_mov_b32 s4, 0x4038aa3b
	v_mul_f32_e64 v26, |v25|, s4
	v_exp_f32_e32 v26, v26
	s_nop 0
	v_add_f32_e32 v26, 1.0, v26
	v_rcp_f32_e32 v26, v26
	s_nop 0
	v_fma_f32 v26, v26, -2.0, 1.0
	s_brev_b32 s4, -2
	v_bfi_b32 v21, s4, v24, v21
	v_mul_f32_e32 v22, 0.5, v22
	v_add_f32_e32 v21, 1.0, v21
	v_mul_f32_e32 v21, v22, v21
	v_mul_f32_e32 v22, 0.5, v23
	v_bfi_b32 v23, s4, v26, v25
	v_add_f32_e32 v23, 1.0, v23
	v_mul_f32_e32 v22, v22, v23
	v_cvt_pk_bf16_f32 v21, v21, v22
	v_or_b32_e32 v22, 2, v30
	v_ashrrev_i32_e32 v23, 31, v22
	v_lshlrev_b64 v[22:23], 11, v[22:23]
	v_lshl_add_u64 v[22:23], v[28:29], 0, v[22:23]
	global_store_dwordx2 v[22:23], v[20:21], off
	v_mul_f32_e32 v20, 0x3d372713, v16
	v_mul_f32_e32 v20, v16, v20
	v_fma_f32 v20, v16, v20, v16
	v_mul_f32_e32 v20, 0x3f4c422a, v20
	s_mov_b32 s4, 0x4038aa3b
	v_mul_f32_e64 v21, |v20|, s4
	v_exp_f32_e32 v21, v21
	s_nop 0
	v_add_f32_e32 v21, 1.0, v21
	v_rcp_f32_e32 v21, v21
	s_nop 0
	v_fma_f32 v21, v21, -2.0, 1.0
	v_mul_f32_e32 v22, 0x3d372713, v17
	v_mul_f32_e32 v22, v17, v22
	v_fma_f32 v22, v17, v22, v17
	v_mul_f32_e32 v22, 0x3f4c422a, v22
	s_mov_b32 s4, 0x4038aa3b
	v_mul_f32_e64 v23, |v22|, s4
	v_exp_f32_e32 v23, v23
	s_nop 0
	v_add_f32_e32 v23, 1.0, v23
	v_rcp_f32_e32 v23, v23
	s_nop 0
	v_fma_f32 v23, v23, -2.0, 1.0
	s_brev_b32 s4, -2
	v_bfi_b32 v20, s4, v21, v20
	v_mul_f32_e32 v16, 0.5, v16
	v_add_f32_e32 v20, 1.0, v20
	v_mul_f32_e32 v16, v16, v20
	v_bfi_b32 v20, s4, v23, v22
	v_mul_f32_e32 v17, 0.5, v17
	v_add_f32_e32 v20, 1.0, v20
	v_mul_f32_e32 v17, v17, v20
	v_cvt_pk_bf16_f32 v16, v16, v17
	v_mul_f32_e32 v17, 0x3d372713, v18
	v_mul_f32_e32 v17, v18, v17
	v_fma_f32 v17, v18, v17, v18
	v_mul_f32_e32 v17, 0x3f4c422a, v17
	s_mov_b32 s4, 0x4038aa3b
	v_mul_f32_e64 v20, |v17|, s4
	v_exp_f32_e32 v20, v20
	s_nop 0
	v_add_f32_e32 v20, 1.0, v20
	v_rcp_f32_e32 v20, v20
	s_nop 0
	v_fma_f32 v20, v20, -2.0, 1.0
	v_mul_f32_e32 v21, 0x3d372713, v19
	v_mul_f32_e32 v21, v19, v21
	v_fma_f32 v21, v19, v21, v19
	v_mul_f32_e32 v21, 0x3f4c422a, v21
	s_mov_b32 s4, 0x4038aa3b
	v_mul_f32_e64 v22, |v21|, s4
	v_exp_f32_e32 v22, v22
	s_nop 0
	v_add_f32_e32 v22, 1.0, v22
	v_rcp_f32_e32 v22, v22
	s_nop 0
	v_fma_f32 v22, v22, -2.0, 1.0
	s_brev_b32 s4, -2
	v_bfi_b32 v17, s4, v20, v17
	v_mul_f32_e32 v18, 0.5, v18
	v_add_f32_e32 v17, 1.0, v17
	v_mul_f32_e32 v17, v18, v17
	v_mul_f32_e32 v18, 0.5, v19
	v_bfi_b32 v19, s4, v22, v21
	v_add_f32_e32 v19, 1.0, v19
	v_mul_f32_e32 v18, v18, v19
	v_cvt_pk_bf16_f32 v17, v17, v18
	v_or_b32_e32 v18, 3, v30
	v_ashrrev_i32_e32 v19, 31, v18
	v_lshlrev_b64 v[18:19], 11, v[18:19]
	v_lshl_add_u64 v[18:19], v[28:29], 0, v[18:19]
	global_store_dwordx2 v[18:19], v[16:17], off
	v_mul_f32_e32 v16, 0x3d372713, v12
	v_mul_f32_e32 v16, v12, v16
	v_fma_f32 v16, v12, v16, v12
	v_mul_f32_e32 v16, 0x3f4c422a, v16
	s_mov_b32 s4, 0x4038aa3b
	v_mul_f32_e64 v17, |v16|, s4
	v_exp_f32_e32 v17, v17
	s_nop 0
	v_add_f32_e32 v17, 1.0, v17
	v_rcp_f32_e32 v17, v17
	s_nop 0
	v_fma_f32 v17, v17, -2.0, 1.0
	v_mul_f32_e32 v18, 0x3d372713, v13
	v_mul_f32_e32 v18, v13, v18
	v_fma_f32 v18, v13, v18, v13
	v_mul_f32_e32 v18, 0x3f4c422a, v18
	s_mov_b32 s4, 0x4038aa3b
	v_mul_f32_e64 v19, |v18|, s4
	v_exp_f32_e32 v19, v19
	s_nop 0
	v_add_f32_e32 v19, 1.0, v19
	v_rcp_f32_e32 v19, v19
	s_nop 0
	v_fma_f32 v19, v19, -2.0, 1.0
	s_brev_b32 s4, -2
	v_bfi_b32 v16, s4, v17, v16
	v_mul_f32_e32 v12, 0.5, v12
	v_add_f32_e32 v16, 1.0, v16
	v_mul_f32_e32 v12, v12, v16
	v_bfi_b32 v16, s4, v19, v18
	v_mul_f32_e32 v13, 0.5, v13
	v_add_f32_e32 v16, 1.0, v16
	v_mul_f32_e32 v13, v13, v16
	v_cvt_pk_bf16_f32 v12, v12, v13
	v_mul_f32_e32 v13, 0x3d372713, v14
	v_mul_f32_e32 v13, v14, v13
	v_fma_f32 v13, v14, v13, v14
	v_mul_f32_e32 v13, 0x3f4c422a, v13
	s_mov_b32 s4, 0x4038aa3b
	v_mul_f32_e64 v16, |v13|, s4
	v_exp_f32_e32 v16, v16
	s_nop 0
	v_add_f32_e32 v16, 1.0, v16
	v_rcp_f32_e32 v16, v16
	s_nop 0
	v_fma_f32 v16, v16, -2.0, 1.0
	v_mul_f32_e32 v17, 0x3d372713, v15
	v_mul_f32_e32 v17, v15, v17
	v_fma_f32 v17, v15, v17, v15
	v_mul_f32_e32 v17, 0x3f4c422a, v17
	s_mov_b32 s4, 0x4038aa3b
	v_mul_f32_e64 v18, |v17|, s4
	v_exp_f32_e32 v18, v18
	s_nop 0
	v_add_f32_e32 v18, 1.0, v18
	v_rcp_f32_e32 v18, v18
	s_nop 0
	v_fma_f32 v18, v18, -2.0, 1.0
	s_brev_b32 s4, -2
	v_bfi_b32 v13, s4, v16, v13
	v_mul_f32_e32 v14, 0.5, v14
	v_add_f32_e32 v13, 1.0, v13
	v_mul_f32_e32 v13, v14, v13
	v_mul_f32_e32 v14, 0.5, v15
	v_bfi_b32 v15, s4, v18, v17
	v_add_f32_e32 v15, 1.0, v15
	v_mul_f32_e32 v14, v14, v15
	v_cvt_pk_bf16_f32 v13, v13, v14
	v_or_b32_e32 v14, 4, v30
	v_ashrrev_i32_e32 v15, 31, v14
	v_lshlrev_b64 v[14:15], 11, v[14:15]
	v_lshl_add_u64 v[14:15], v[28:29], 0, v[14:15]
	global_store_dwordx2 v[14:15], v[12:13], off
	v_mul_f32_e32 v12, 0x3d372713, v8
	v_mul_f32_e32 v12, v8, v12
	v_fma_f32 v12, v8, v12, v8
	v_mul_f32_e32 v12, 0x3f4c422a, v12
	s_mov_b32 s4, 0x4038aa3b
	v_mul_f32_e64 v13, |v12|, s4
	v_exp_f32_e32 v13, v13
	s_nop 0
	v_add_f32_e32 v13, 1.0, v13
	v_rcp_f32_e32 v13, v13
	s_nop 0
	v_fma_f32 v13, v13, -2.0, 1.0
	v_mul_f32_e32 v14, 0x3d372713, v9
	v_mul_f32_e32 v14, v9, v14
	v_fma_f32 v14, v9, v14, v9
	v_mul_f32_e32 v14, 0x3f4c422a, v14
	s_mov_b32 s4, 0x4038aa3b
	v_mul_f32_e64 v15, |v14|, s4
	v_exp_f32_e32 v15, v15
	s_nop 0
	v_add_f32_e32 v15, 1.0, v15
	v_rcp_f32_e32 v15, v15
	s_nop 0
	v_fma_f32 v15, v15, -2.0, 1.0
	s_brev_b32 s4, -2
	v_bfi_b32 v12, s4, v13, v12
	v_mul_f32_e32 v8, 0.5, v8
	v_add_f32_e32 v12, 1.0, v12
	v_mul_f32_e32 v8, v8, v12
	v_bfi_b32 v12, s4, v15, v14
	v_mul_f32_e32 v9, 0.5, v9
	v_add_f32_e32 v12, 1.0, v12
	v_mul_f32_e32 v9, v9, v12
	v_cvt_pk_bf16_f32 v8, v8, v9
	v_mul_f32_e32 v9, 0x3d372713, v10
	v_mul_f32_e32 v9, v10, v9
	v_fma_f32 v9, v10, v9, v10
	v_mul_f32_e32 v9, 0x3f4c422a, v9
	s_mov_b32 s4, 0x4038aa3b
	v_mul_f32_e64 v12, |v9|, s4
	v_exp_f32_e32 v12, v12
	s_nop 0
	v_add_f32_e32 v12, 1.0, v12
	v_rcp_f32_e32 v12, v12
	s_nop 0
	v_fma_f32 v12, v12, -2.0, 1.0
	v_mul_f32_e32 v13, 0x3d372713, v11
	v_mul_f32_e32 v13, v11, v13
	v_fma_f32 v13, v11, v13, v11
	v_mul_f32_e32 v13, 0x3f4c422a, v13
	s_mov_b32 s4, 0x4038aa3b
	v_mul_f32_e64 v14, |v13|, s4
	v_exp_f32_e32 v14, v14
	s_nop 0
	v_add_f32_e32 v14, 1.0, v14
	v_rcp_f32_e32 v14, v14
	s_nop 0
	v_fma_f32 v14, v14, -2.0, 1.0
	s_brev_b32 s4, -2
	v_bfi_b32 v9, s4, v12, v9
	v_mul_f32_e32 v10, 0.5, v10
	v_add_f32_e32 v9, 1.0, v9
	v_mul_f32_e32 v9, v10, v9
	v_mul_f32_e32 v10, 0.5, v11
	v_bfi_b32 v11, s4, v14, v13
	v_add_f32_e32 v11, 1.0, v11
	v_mul_f32_e32 v10, v10, v11
	v_cvt_pk_bf16_f32 v9, v9, v10
	v_or_b32_e32 v10, 5, v30
	v_ashrrev_i32_e32 v11, 31, v10
	v_lshlrev_b64 v[10:11], 11, v[10:11]
	v_lshl_add_u64 v[10:11], v[28:29], 0, v[10:11]
	global_store_dwordx2 v[10:11], v[8:9], off
	v_mul_f32_e32 v8, 0x3d372713, v4
	v_mul_f32_e32 v8, v4, v8
	v_fma_f32 v8, v4, v8, v4
	v_mul_f32_e32 v8, 0x3f4c422a, v8
	s_mov_b32 s4, 0x4038aa3b
	v_mul_f32_e64 v9, |v8|, s4
	v_exp_f32_e32 v9, v9
	s_nop 0
	v_add_f32_e32 v9, 1.0, v9
	v_rcp_f32_e32 v9, v9
	s_nop 0
	v_fma_f32 v9, v9, -2.0, 1.0
	v_mul_f32_e32 v10, 0x3d372713, v5
	v_mul_f32_e32 v10, v5, v10
	v_fma_f32 v10, v5, v10, v5
	v_mul_f32_e32 v10, 0x3f4c422a, v10
	s_mov_b32 s4, 0x4038aa3b
	v_mul_f32_e64 v11, |v10|, s4
	v_exp_f32_e32 v11, v11
	s_nop 0
	v_add_f32_e32 v11, 1.0, v11
	v_rcp_f32_e32 v11, v11
	s_nop 0
	v_fma_f32 v11, v11, -2.0, 1.0
	s_brev_b32 s4, -2
	v_bfi_b32 v8, s4, v9, v8
	v_mul_f32_e32 v4, 0.5, v4
	v_add_f32_e32 v8, 1.0, v8
	v_mul_f32_e32 v4, v4, v8
	v_bfi_b32 v8, s4, v11, v10
	v_mul_f32_e32 v5, 0.5, v5
	v_add_f32_e32 v8, 1.0, v8
	v_mul_f32_e32 v5, v5, v8
	v_cvt_pk_bf16_f32 v4, v4, v5
	v_mul_f32_e32 v5, 0x3d372713, v6
	v_mul_f32_e32 v5, v6, v5
	v_fma_f32 v5, v6, v5, v6
	v_mul_f32_e32 v5, 0x3f4c422a, v5
	s_mov_b32 s4, 0x4038aa3b
	v_mul_f32_e64 v8, |v5|, s4
	v_exp_f32_e32 v8, v8
	s_nop 0
	v_add_f32_e32 v8, 1.0, v8
	v_rcp_f32_e32 v8, v8
	s_nop 0
	v_fma_f32 v8, v8, -2.0, 1.0
	v_mul_f32_e32 v9, 0x3d372713, v7
	v_mul_f32_e32 v9, v7, v9
	v_fma_f32 v9, v7, v9, v7
	v_mul_f32_e32 v9, 0x3f4c422a, v9
	s_mov_b32 s4, 0x4038aa3b
	v_mul_f32_e64 v10, |v9|, s4
	v_exp_f32_e32 v10, v10
	s_nop 0
	v_add_f32_e32 v10, 1.0, v10
	v_rcp_f32_e32 v10, v10
	s_nop 0
	v_fma_f32 v10, v10, -2.0, 1.0
	s_brev_b32 s4, -2
	v_bfi_b32 v5, s4, v8, v5
	v_mul_f32_e32 v6, 0.5, v6
	v_add_f32_e32 v5, 1.0, v5
	v_mul_f32_e32 v5, v6, v5
	v_mul_f32_e32 v6, 0.5, v7
	v_bfi_b32 v7, s4, v10, v9
	v_add_f32_e32 v7, 1.0, v7
	v_mul_f32_e32 v6, v6, v7
	v_cvt_pk_bf16_f32 v5, v5, v6
	v_or_b32_e32 v6, 6, v30
	v_ashrrev_i32_e32 v7, 31, v6
	v_lshlrev_b64 v[6:7], 11, v[6:7]
	v_lshl_add_u64 v[6:7], v[28:29], 0, v[6:7]
	global_store_dwordx2 v[6:7], v[4:5], off
	v_mul_f32_e32 v4, 0x3d372713, v0
	v_mul_f32_e32 v4, v0, v4
	v_fma_f32 v4, v0, v4, v0
	v_mul_f32_e32 v4, 0x3f4c422a, v4
	s_mov_b32 s4, 0x4038aa3b
	v_mul_f32_e64 v5, |v4|, s4
	v_exp_f32_e32 v5, v5
	s_nop 0
	v_add_f32_e32 v5, 1.0, v5
	v_rcp_f32_e32 v5, v5
	s_nop 0
	v_fma_f32 v5, v5, -2.0, 1.0
	v_mul_f32_e32 v6, 0x3d372713, v1
	v_mul_f32_e32 v6, v1, v6
	v_fma_f32 v6, v1, v6, v1
	v_mul_f32_e32 v6, 0x3f4c422a, v6
	s_mov_b32 s4, 0x4038aa3b
	v_mul_f32_e64 v7, |v6|, s4
	v_exp_f32_e32 v7, v7
	s_nop 0
	v_add_f32_e32 v7, 1.0, v7
	v_rcp_f32_e32 v7, v7
	s_nop 0
	v_fma_f32 v7, v7, -2.0, 1.0
	s_brev_b32 s4, -2
	v_bfi_b32 v4, s4, v5, v4
	v_mul_f32_e32 v0, 0.5, v0
	v_add_f32_e32 v4, 1.0, v4
	v_mul_f32_e32 v0, v0, v4
	v_bfi_b32 v4, s4, v7, v6
	v_mul_f32_e32 v1, 0.5, v1
	v_add_f32_e32 v4, 1.0, v4
	v_mul_f32_e32 v1, v1, v4
	v_cvt_pk_bf16_f32 v0, v0, v1
	v_mul_f32_e32 v1, 0x3d372713, v2
	v_mul_f32_e32 v1, v2, v1
	v_fma_f32 v1, v2, v1, v2
	v_mul_f32_e32 v1, 0x3f4c422a, v1
	s_mov_b32 s4, 0x4038aa3b
	v_mul_f32_e64 v4, |v1|, s4
	v_exp_f32_e32 v4, v4
	s_nop 0
	v_add_f32_e32 v4, 1.0, v4
	v_rcp_f32_e32 v4, v4
	s_nop 0
	v_fma_f32 v4, v4, -2.0, 1.0
	v_mul_f32_e32 v5, 0x3d372713, v3
	v_mul_f32_e32 v5, v3, v5
	v_fma_f32 v5, v3, v5, v3
	v_mul_f32_e32 v5, 0x3f4c422a, v5
	s_mov_b32 s4, 0x3f200000
	v_cmp_nlt_f32_e64 s[4:5], |v5|, s4
	s_and_saveexec_b64 s[6:7], s[4:5]
	s_xor_b64 s[4:5], exec, s[6:7]
	s_cbranch_execz .LBB0_778
	v_add_f32_e64 v6, |v5|, |v5|
	v_mul_f32_e32 v7, 0x3fb8aa3b, v6
	v_rndne_f32_e32 v8, v7
	s_mov_b32 s6, 0x3fb8aa3b
	v_sub_f32_e32 v9, v7, v8
	v_fma_f32 v7, v6, s6, -v7
	v_fmac_f32_e32 v7, 0x32a5705f, v6
	v_add_f32_e32 v7, v9, v7
	v_cvt_i32_f32_e32 v8, v8
	v_exp_f32_e32 v7, v7
	s_mov_b32 s6, 0xc2ce8ed0
	v_cmp_ngt_f32_e32 vcc, s6, v6
	s_mov_b32 s6, 0x42b17218
	v_ldexp_f32 v7, v7, v8
	v_cndmask_b32_e32 v7, 0, v7, vcc
	v_cmp_nlt_f32_e32 vcc, s6, v6
	s_nop 1
	v_cndmask_b32_e32 v6, v231, v7, vcc
	v_add_f32_e32 v6, 1.0, v6
	v_rcp_f32_e32 v6, v6
	s_nop 0
	v_fma_f32 v6, v6, -2.0, 1.0
